# k24: k23 + S5 carry-chain item hand-written (chunk states loaded once with a rolling window of 60 loads and kept in registers for the second pass)
# speedup vs baseline: 1.0101x; 1.0065x over previous
; #define LAS __attribute__((address_space(3)))
; #define TIDS() const int tid = fresh_tid(), lane = tid & 63, wave = __builtin_amdgcn_readfirstlane(tid >> 6); (void)lane; (void)wave
; __device__ __forceinline__ f32x2 cmul(f32x2 a, f32x2 b) { return (f32x2){a.x * b.x - a.y * b.y, a.x * b.y + a.y * b.x}; }
; #define SB WSP(float, WS_SB)
; __global__ void __launch_bounds__(NTHR, 2) hymba_fwd(Params P) {
;     ...
;     for (int repc = 0; repc < REP_CH; ++repc) {
;     for (int it = blk; it < NB * NG; it += G) {
;         TIDS();
;         const int b = it >> 5, g = it & 31, n = lane, w = wave;
;         LAS f32x2* EE = (LAS f32x2*)lds;
;         const f32x2 a16 = A16[g * 64 + n];
;         const float* sp = SB + ((size_t)g * NCH + b * 512 + w * 64) * 128;
;         f32x2 e = {0.f, 0.f};
; #pragma unroll 32
;         for (int c = 0; c < 64; ++c) { const f32x2 s = {sp[c * 128 + n], sp[c * 128 + 64 + n]}; const f32x2 ax = cmul(a16, e); e = (f32x2){ax.x + s.x, ax.y + s.y}; }
.LBB0_695:
	s_and_b64 vcc, exec, s[0:1]
	s_cbranch_vccnz .LBB0_713
	v_mov_b32_e32 v0, v208
	v_and_b32_e32 v2, 63, v0
	s_and_b32 s4, s2, 31
	v_lshlrev_b32_e32 v3, 3, v2
	v_lshl_or_b32 v3, s4, 9, v3
	global_load_dwordx2 v[4:5], v3, s[70:71]
	v_readfirstlane_b32 s12, v0
	s_lshr_b32 s5, s2, 5
	s_lshl_b32 s5, s5, 9
	s_lshr_b32 s12, s12, 6
	s_lshl_b32 s6, s12, 6
	s_add_i32 s5, s5, s6
	s_lshl_b32 s7, s5, 9
	s_lshl_b32 s8, s4, 21
	s_add_u32 s8, s8, s7
	s_add_u32 s8, s8, 0x27300000
	s_add_u32 s8, s92, s8
	s_addc_u32 s9, s93, 0
	v_lshlrev_b32_e32 v40, 2, v2
	v_add_u32_e32 v41, 0x1000, v40
	v_add_u32_e32 v42, 0x2000, v40
	v_add_u32_e32 v43, 0x3000, v40
	v_add_u32_e32 v44, 0x4000, v40
	v_add_u32_e32 v45, 0x5000, v40
	v_add_u32_e32 v46, 0x6000, v40
	v_add_u32_e32 v47, 0x7000, v40
	global_load_dword v64, v40, s[8:9]
	global_load_dword v65, v40, s[8:9] offset:256
	global_load_dword v66, v40, s[8:9] offset:512
	global_load_dword v67, v40, s[8:9] offset:768
	global_load_dword v68, v40, s[8:9] offset:1024
	global_load_dword v69, v40, s[8:9] offset:1280
	global_load_dword v70, v40, s[8:9] offset:1536
	global_load_dword v71, v40, s[8:9] offset:1792
	global_load_dword v72, v40, s[8:9] offset:2048
	global_load_dword v73, v40, s[8:9] offset:2304
	global_load_dword v74, v40, s[8:9] offset:2560
	global_load_dword v75, v40, s[8:9] offset:2816
	global_load_dword v76, v40, s[8:9] offset:3072
	global_load_dword v77, v40, s[8:9] offset:3328
	global_load_dword v78, v40, s[8:9] offset:3584
	global_load_dword v79, v40, s[8:9] offset:3840
	global_load_dword v80, v41, s[8:9]
	global_load_dword v81, v41, s[8:9] offset:256
	global_load_dword v82, v41, s[8:9] offset:512
	global_load_dword v83, v41, s[8:9] offset:768
	global_load_dword v84, v41, s[8:9] offset:1024
	global_load_dword v85, v41, s[8:9] offset:1280
	global_load_dword v86, v41, s[8:9] offset:1536
	global_load_dword v87, v41, s[8:9] offset:1792
	global_load_dword v88, v41, s[8:9] offset:2048
	global_load_dword v89, v41, s[8:9] offset:2304
	global_load_dword v90, v41, s[8:9] offset:2560
	global_load_dword v91, v41, s[8:9] offset:2816
	global_load_dword v92, v41, s[8:9] offset:3072
	global_load_dword v93, v41, s[8:9] offset:3328
	global_load_dword v94, v41, s[8:9] offset:3584
	global_load_dword v95, v41, s[8:9] offset:3840
	global_load_dword v96, v42, s[8:9]
	global_load_dword v97, v42, s[8:9] offset:256
	global_load_dword v98, v42, s[8:9] offset:512
	global_load_dword v99, v42, s[8:9] offset:768
	global_load_dword v100, v42, s[8:9] offset:1024
	global_load_dword v101, v42, s[8:9] offset:1280
	global_load_dword v102, v42, s[8:9] offset:1536
	global_load_dword v103, v42, s[8:9] offset:1792
	global_load_dword v104, v42, s[8:9] offset:2048
	global_load_dword v105, v42, s[8:9] offset:2304
	global_load_dword v106, v42, s[8:9] offset:2560
	global_load_dword v107, v42, s[8:9] offset:2816
	global_load_dword v108, v42, s[8:9] offset:3072
	global_load_dword v109, v42, s[8:9] offset:3328
	global_load_dword v110, v42, s[8:9] offset:3584
	global_load_dword v111, v42, s[8:9] offset:3840
	global_load_dword v112, v43, s[8:9]
	global_load_dword v113, v43, s[8:9] offset:256
	global_load_dword v114, v43, s[8:9] offset:512
	global_load_dword v115, v43, s[8:9] offset:768
	global_load_dword v116, v43, s[8:9] offset:1024
	global_load_dword v117, v43, s[8:9] offset:1280
	global_load_dword v118, v43, s[8:9] offset:1536
	global_load_dword v119, v43, s[8:9] offset:1792
	global_load_dword v120, v43, s[8:9] offset:2048
	global_load_dword v121, v43, s[8:9] offset:2304
	global_load_dword v122, v43, s[8:9] offset:2560
	global_load_dword v123, v43, s[8:9] offset:2816
	s_mul_i32 s6, s4, 0x306000
	s_mul_i32 s7, s5, 0x300
	s_add_u32 s10, s22, s6
	s_addc_u32 s11, s23, 0
	s_add_u32 s10, s10, s7
	s_addc_u32 s11, s11, 0
	v_lshlrev_b32_e32 v6, 1, v2
	v_add_u32_e32 v6, 0x200, v6
	v_lshl_add_u32 v7, s12, 6, v2
	v_lshlrev_b32_e32 v7, 3, v7
	s_movk_i32 s35, 0x7fff
	v_mov_b32_e32 v8, 0
	v_mov_b32_e32 v9, 0
	s_waitcnt vmcnt(58)
	v_mul_f32_e32 v12, v5, v9
	v_mul_f32_e32 v14, v4, v9
	v_fma_f32 v12, v4, v8, -v12
	v_fma_f32 v14, v5, v8, v14
	v_add_f32_e32 v8, v12, v64
	v_add_f32_e32 v9, v14, v65
	global_load_dword v124, v43, s[8:9] offset:3072
	global_load_dword v125, v43, s[8:9] offset:3328
	s_waitcnt vmcnt(58)
	v_mul_f32_e32 v12, v5, v9
	v_mul_f32_e32 v14, v4, v9
	v_fma_f32 v12, v4, v8, -v12
	v_fma_f32 v14, v5, v8, v14
	v_add_f32_e32 v8, v12, v66
	v_add_f32_e32 v9, v14, v67
	global_load_dword v126, v43, s[8:9] offset:3584
	global_load_dword v127, v43, s[8:9] offset:3840
	s_waitcnt vmcnt(58)
	v_mul_f32_e32 v12, v5, v9
	v_mul_f32_e32 v14, v4, v9
	v_fma_f32 v12, v4, v8, -v12
	v_fma_f32 v14, v5, v8, v14
	v_add_f32_e32 v8, v12, v68
	v_add_f32_e32 v9, v14, v69
	global_load_dword v128, v44, s[8:9]
	global_load_dword v129, v44, s[8:9] offset:256
	s_waitcnt vmcnt(58)
	v_mul_f32_e32 v12, v5, v9
	v_mul_f32_e32 v14, v4, v9
	v_fma_f32 v12, v4, v8, -v12
	v_fma_f32 v14, v5, v8, v14
	v_add_f32_e32 v8, v12, v70
	v_add_f32_e32 v9, v14, v71
	global_load_dword v130, v44, s[8:9] offset:512
	global_load_dword v131, v44, s[8:9] offset:768
	s_waitcnt vmcnt(58)
	v_mul_f32_e32 v12, v5, v9
	v_mul_f32_e32 v14, v4, v9
	v_fma_f32 v12, v4, v8, -v12
	v_fma_f32 v14, v5, v8, v14
	v_add_f32_e32 v8, v12, v72
	v_add_f32_e32 v9, v14, v73
	global_load_dword v132, v44, s[8:9] offset:1024
	global_load_dword v133, v44, s[8:9] offset:1280
	s_waitcnt vmcnt(58)
	v_mul_f32_e32 v12, v5, v9
	v_mul_f32_e32 v14, v4, v9
	v_fma_f32 v12, v4, v8, -v12
	v_fma_f32 v14, v5, v8, v14
	v_add_f32_e32 v8, v12, v74
	v_add_f32_e32 v9, v14, v75
	global_load_dword v134, v44, s[8:9] offset:1536
	global_load_dword v135, v44, s[8:9] offset:1792
	s_waitcnt vmcnt(58)
; __device__ __forceinline__ f32x2 cmul(f32x2 a, f32x2 b) { return (f32x2){a.x * b.x - a.y * b.y, a.x * b.y + a.y * b.x}; }
; __global__ void __launch_bounds__(NTHR, 2) hymba_fwd(Params P) {
;     ...
;         f32x2 e = {0.f, 0.f};
; #pragma unroll 32
;         for (int c = 0; c < 64; ++c) { const f32x2 s = {sp[c * 128 + n], sp[c * 128 + 64 + n]}; const f32x2 ax = cmul(a16, e); e = (f32x2){ax.x + s.x, ax.y + s.y}; }
	v_mul_f32_e32 v12, v5, v9
	v_mul_f32_e32 v14, v4, v9
	v_fma_f32 v12, v4, v8, -v12
	v_fma_f32 v14, v5, v8, v14
	v_add_f32_e32 v8, v12, v76
	v_add_f32_e32 v9, v14, v77
	global_load_dword v136, v44, s[8:9] offset:2048
	global_load_dword v137, v44, s[8:9] offset:2304
	s_waitcnt vmcnt(58)
	v_mul_f32_e32 v12, v5, v9
	v_mul_f32_e32 v14, v4, v9
	v_fma_f32 v12, v4, v8, -v12
	v_fma_f32 v14, v5, v8, v14
	v_add_f32_e32 v8, v12, v78
	v_add_f32_e32 v9, v14, v79
	global_load_dword v138, v44, s[8:9] offset:2560
	global_load_dword v139, v44, s[8:9] offset:2816
	s_waitcnt vmcnt(58)
	v_mul_f32_e32 v12, v5, v9
	v_mul_f32_e32 v14, v4, v9
	v_fma_f32 v12, v4, v8, -v12
	v_fma_f32 v14, v5, v8, v14
	v_add_f32_e32 v8, v12, v80
	v_add_f32_e32 v9, v14, v81
	global_load_dword v140, v44, s[8:9] offset:3072
	global_load_dword v141, v44, s[8:9] offset:3328
	s_waitcnt vmcnt(58)
	v_mul_f32_e32 v12, v5, v9
	v_mul_f32_e32 v14, v4, v9
	v_fma_f32 v12, v4, v8, -v12
	v_fma_f32 v14, v5, v8, v14
	v_add_f32_e32 v8, v12, v82
	v_add_f32_e32 v9, v14, v83
	global_load_dword v142, v44, s[8:9] offset:3584
	global_load_dword v143, v44, s[8:9] offset:3840
	s_waitcnt vmcnt(58)
	v_mul_f32_e32 v12, v5, v9
	v_mul_f32_e32 v14, v4, v9
	v_fma_f32 v12, v4, v8, -v12
	v_fma_f32 v14, v5, v8, v14
	v_add_f32_e32 v8, v12, v84
	v_add_f32_e32 v9, v14, v85
	global_load_dword v144, v45, s[8:9]
	global_load_dword v145, v45, s[8:9] offset:256
	s_waitcnt vmcnt(58)
	v_mul_f32_e32 v12, v5, v9
	v_mul_f32_e32 v14, v4, v9
	v_fma_f32 v12, v4, v8, -v12
	v_fma_f32 v14, v5, v8, v14
	v_add_f32_e32 v8, v12, v86
	v_add_f32_e32 v9, v14, v87
	global_load_dword v146, v45, s[8:9] offset:512
	global_load_dword v147, v45, s[8:9] offset:768
	s_waitcnt vmcnt(58)
	v_mul_f32_e32 v12, v5, v9
	v_mul_f32_e32 v14, v4, v9
	v_fma_f32 v12, v4, v8, -v12
	v_fma_f32 v14, v5, v8, v14
	v_add_f32_e32 v8, v12, v88
	v_add_f32_e32 v9, v14, v89
	global_load_dword v148, v45, s[8:9] offset:1024
	global_load_dword v149, v45, s[8:9] offset:1280
	s_waitcnt vmcnt(58)
	v_mul_f32_e32 v12, v5, v9
	v_mul_f32_e32 v14, v4, v9
	v_fma_f32 v12, v4, v8, -v12
	v_fma_f32 v14, v5, v8, v14
	v_add_f32_e32 v8, v12, v90
	v_add_f32_e32 v9, v14, v91
	global_load_dword v150, v45, s[8:9] offset:1536
	global_load_dword v151, v45, s[8:9] offset:1792
	s_waitcnt vmcnt(58)
	v_mul_f32_e32 v12, v5, v9
	v_mul_f32_e32 v14, v4, v9
	v_fma_f32 v12, v4, v8, -v12
	v_fma_f32 v14, v5, v8, v14
	v_add_f32_e32 v8, v12, v92
	v_add_f32_e32 v9, v14, v93
	global_load_dword v152, v45, s[8:9] offset:2048
	global_load_dword v153, v45, s[8:9] offset:2304
	s_waitcnt vmcnt(58)
	v_mul_f32_e32 v12, v5, v9
	v_mul_f32_e32 v14, v4, v9
	v_fma_f32 v12, v4, v8, -v12
	v_fma_f32 v14, v5, v8, v14
	v_add_f32_e32 v8, v12, v94
	v_add_f32_e32 v9, v14, v95
	global_load_dword v154, v45, s[8:9] offset:2560
	global_load_dword v155, v45, s[8:9] offset:2816
	s_waitcnt vmcnt(58)
	v_mul_f32_e32 v12, v5, v9
	v_mul_f32_e32 v14, v4, v9
	v_fma_f32 v12, v4, v8, -v12
	v_fma_f32 v14, v5, v8, v14
	v_add_f32_e32 v8, v12, v96
	v_add_f32_e32 v9, v14, v97
	global_load_dword v156, v45, s[8:9] offset:3072
	global_load_dword v157, v45, s[8:9] offset:3328
	s_waitcnt vmcnt(58)
	v_mul_f32_e32 v12, v5, v9
	v_mul_f32_e32 v14, v4, v9
	v_fma_f32 v12, v4, v8, -v12
	v_fma_f32 v14, v5, v8, v14
	v_add_f32_e32 v8, v12, v98
	v_add_f32_e32 v9, v14, v99
	global_load_dword v158, v45, s[8:9] offset:3584
	global_load_dword v159, v45, s[8:9] offset:3840
	s_waitcnt vmcnt(58)
	v_mul_f32_e32 v12, v5, v9
	v_mul_f32_e32 v14, v4, v9
	v_fma_f32 v12, v4, v8, -v12
	v_fma_f32 v14, v5, v8, v14
	v_add_f32_e32 v8, v12, v100
	v_add_f32_e32 v9, v14, v101
	global_load_dword v160, v46, s[8:9]
	global_load_dword v161, v46, s[8:9] offset:256
	s_waitcnt vmcnt(58)
	v_mul_f32_e32 v12, v5, v9
	v_mul_f32_e32 v14, v4, v9
	v_fma_f32 v12, v4, v8, -v12
	v_fma_f32 v14, v5, v8, v14
	v_add_f32_e32 v8, v12, v102
	v_add_f32_e32 v9, v14, v103
	global_load_dword v162, v46, s[8:9] offset:512
	global_load_dword v163, v46, s[8:9] offset:768
	s_waitcnt vmcnt(58)
	v_mul_f32_e32 v12, v5, v9
	v_mul_f32_e32 v14, v4, v9
	v_fma_f32 v12, v4, v8, -v12
	v_fma_f32 v14, v5, v8, v14
	v_add_f32_e32 v8, v12, v104
	v_add_f32_e32 v9, v14, v105
	global_load_dword v164, v46, s[8:9] offset:1024
	global_load_dword v165, v46, s[8:9] offset:1280
	s_waitcnt vmcnt(58)
	v_mul_f32_e32 v12, v5, v9
	v_mul_f32_e32 v14, v4, v9
	v_fma_f32 v12, v4, v8, -v12
	v_fma_f32 v14, v5, v8, v14
	v_add_f32_e32 v8, v12, v106
	v_add_f32_e32 v9, v14, v107
	global_load_dword v166, v46, s[8:9] offset:1536
	global_load_dword v167, v46, s[8:9] offset:1792
	s_waitcnt vmcnt(58)
	v_mul_f32_e32 v12, v5, v9
	v_mul_f32_e32 v14, v4, v9
	v_fma_f32 v12, v4, v8, -v12
	v_fma_f32 v14, v5, v8, v14
	v_add_f32_e32 v8, v12, v108
	v_add_f32_e32 v9, v14, v109
	global_load_dword v168, v46, s[8:9] offset:2048
	global_load_dword v169, v46, s[8:9] offset:2304
	s_waitcnt vmcnt(58)
	v_mul_f32_e32 v12, v5, v9
	v_mul_f32_e32 v14, v4, v9
	v_fma_f32 v12, v4, v8, -v12
	v_fma_f32 v14, v5, v8, v14
	v_add_f32_e32 v8, v12, v110
	v_add_f32_e32 v9, v14, v111
	global_load_dword v170, v46, s[8:9] offset:2560
	global_load_dword v171, v46, s[8:9] offset:2816
	s_waitcnt vmcnt(58)
	v_mul_f32_e32 v12, v5, v9
	v_mul_f32_e32 v14, v4, v9
	v_fma_f32 v12, v4, v8, -v12
	v_fma_f32 v14, v5, v8, v14
	v_add_f32_e32 v8, v12, v112
	v_add_f32_e32 v9, v14, v113
	global_load_dword v172, v46, s[8:9] offset:3072
	global_load_dword v173, v46, s[8:9] offset:3328
	s_waitcnt vmcnt(58)
	v_mul_f32_e32 v12, v5, v9
	v_mul_f32_e32 v14, v4, v9
	v_fma_f32 v12, v4, v8, -v12
	v_fma_f32 v14, v5, v8, v14
	v_add_f32_e32 v8, v12, v114
	v_add_f32_e32 v9, v14, v115
	global_load_dword v174, v46, s[8:9] offset:3584
	global_load_dword v175, v46, s[8:9] offset:3840
	s_waitcnt vmcnt(58)
; __device__ __forceinline__ f32x2 cmul(f32x2 a, f32x2 b) { return (f32x2){a.x * b.x - a.y * b.y, a.x * b.y + a.y * b.x}; }
; __global__ void __launch_bounds__(NTHR, 2) hymba_fwd(Params P) {
;     ...
;         f32x2 e = {0.f, 0.f};
; #pragma unroll 32
;         for (int c = 0; c < 64; ++c) { const f32x2 s = {sp[c * 128 + n], sp[c * 128 + 64 + n]}; const f32x2 ax = cmul(a16, e); e = (f32x2){ax.x + s.x, ax.y + s.y}; }
	v_mul_f32_e32 v12, v5, v9
	v_mul_f32_e32 v14, v4, v9
	v_fma_f32 v12, v4, v8, -v12
	v_fma_f32 v14, v5, v8, v14
	v_add_f32_e32 v8, v12, v116
	v_add_f32_e32 v9, v14, v117
	global_load_dword v176, v47, s[8:9]
	global_load_dword v177, v47, s[8:9] offset:256
	s_waitcnt vmcnt(58)
	v_mul_f32_e32 v12, v5, v9
	v_mul_f32_e32 v14, v4, v9
	v_fma_f32 v12, v4, v8, -v12
	v_fma_f32 v14, v5, v8, v14
	v_add_f32_e32 v8, v12, v118
	v_add_f32_e32 v9, v14, v119
	global_load_dword v178, v47, s[8:9] offset:512
	global_load_dword v179, v47, s[8:9] offset:768
	s_waitcnt vmcnt(58)
	v_mul_f32_e32 v12, v5, v9
	v_mul_f32_e32 v14, v4, v9
	v_fma_f32 v12, v4, v8, -v12
	v_fma_f32 v14, v5, v8, v14
	v_add_f32_e32 v8, v12, v120
	v_add_f32_e32 v9, v14, v121
	global_load_dword v180, v47, s[8:9] offset:1024
	global_load_dword v181, v47, s[8:9] offset:1280
	s_waitcnt vmcnt(58)
	v_mul_f32_e32 v12, v5, v9
	v_mul_f32_e32 v14, v4, v9
	v_fma_f32 v12, v4, v8, -v12
	v_fma_f32 v14, v5, v8, v14
	v_add_f32_e32 v8, v12, v122
	v_add_f32_e32 v9, v14, v123
	global_load_dword v182, v47, s[8:9] offset:1536
	global_load_dword v183, v47, s[8:9] offset:1792
	s_waitcnt vmcnt(58)
	v_mul_f32_e32 v12, v5, v9
	v_mul_f32_e32 v14, v4, v9
	v_fma_f32 v12, v4, v8, -v12
	v_fma_f32 v14, v5, v8, v14
	v_add_f32_e32 v8, v12, v124
	v_add_f32_e32 v9, v14, v125
	global_load_dword v184, v47, s[8:9] offset:2048
	global_load_dword v185, v47, s[8:9] offset:2304
	s_waitcnt vmcnt(58)
	v_mul_f32_e32 v12, v5, v9
	v_mul_f32_e32 v14, v4, v9
	v_fma_f32 v12, v4, v8, -v12
	v_fma_f32 v14, v5, v8, v14
	v_add_f32_e32 v8, v12, v126
	v_add_f32_e32 v9, v14, v127
	global_load_dword v186, v47, s[8:9] offset:2560
	global_load_dword v187, v47, s[8:9] offset:2816
	s_waitcnt vmcnt(58)
	v_mul_f32_e32 v12, v5, v9
	v_mul_f32_e32 v14, v4, v9
	v_fma_f32 v12, v4, v8, -v12
	v_fma_f32 v14, v5, v8, v14
	v_add_f32_e32 v8, v12, v128
	v_add_f32_e32 v9, v14, v129
	global_load_dword v188, v47, s[8:9] offset:3072
	global_load_dword v189, v47, s[8:9] offset:3328
	s_waitcnt vmcnt(58)
	v_mul_f32_e32 v12, v5, v9
	v_mul_f32_e32 v14, v4, v9
	v_fma_f32 v12, v4, v8, -v12
	v_fma_f32 v14, v5, v8, v14
	v_add_f32_e32 v8, v12, v130
	v_add_f32_e32 v9, v14, v131
	global_load_dword v190, v47, s[8:9] offset:3584
	global_load_dword v191, v47, s[8:9] offset:3840
	s_waitcnt vmcnt(58)
	v_mul_f32_e32 v12, v5, v9
	v_mul_f32_e32 v14, v4, v9
	v_fma_f32 v12, v4, v8, -v12
	v_fma_f32 v14, v5, v8, v14
	v_add_f32_e32 v8, v12, v132
	v_add_f32_e32 v9, v14, v133
	s_waitcnt vmcnt(56)
	v_mul_f32_e32 v12, v5, v9
	v_mul_f32_e32 v14, v4, v9
	v_fma_f32 v12, v4, v8, -v12
	v_fma_f32 v14, v5, v8, v14
	v_add_f32_e32 v8, v12, v134
	v_add_f32_e32 v9, v14, v135
	s_waitcnt vmcnt(54)
	v_mul_f32_e32 v12, v5, v9
	v_mul_f32_e32 v14, v4, v9
	v_fma_f32 v12, v4, v8, -v12
	v_fma_f32 v14, v5, v8, v14
	v_add_f32_e32 v8, v12, v136
	v_add_f32_e32 v9, v14, v137
	s_waitcnt vmcnt(52)
	v_mul_f32_e32 v12, v5, v9
	v_mul_f32_e32 v14, v4, v9
	v_fma_f32 v12, v4, v8, -v12
	v_fma_f32 v14, v5, v8, v14
	v_add_f32_e32 v8, v12, v138
	v_add_f32_e32 v9, v14, v139
	s_waitcnt vmcnt(50)
	v_mul_f32_e32 v12, v5, v9
	v_mul_f32_e32 v14, v4, v9
	v_fma_f32 v12, v4, v8, -v12
	v_fma_f32 v14, v5, v8, v14
	v_add_f32_e32 v8, v12, v140
	v_add_f32_e32 v9, v14, v141
	s_waitcnt vmcnt(48)
	v_mul_f32_e32 v12, v5, v9
	v_mul_f32_e32 v14, v4, v9
	v_fma_f32 v12, v4, v8, -v12
	v_fma_f32 v14, v5, v8, v14
	v_add_f32_e32 v8, v12, v142
	v_add_f32_e32 v9, v14, v143
	s_waitcnt vmcnt(46)
	v_mul_f32_e32 v12, v5, v9
	v_mul_f32_e32 v14, v4, v9
	v_fma_f32 v12, v4, v8, -v12
	v_fma_f32 v14, v5, v8, v14
	v_add_f32_e32 v8, v12, v144
	v_add_f32_e32 v9, v14, v145
	s_waitcnt vmcnt(44)
	v_mul_f32_e32 v12, v5, v9
	v_mul_f32_e32 v14, v4, v9
	v_fma_f32 v12, v4, v8, -v12
	v_fma_f32 v14, v5, v8, v14
	v_add_f32_e32 v8, v12, v146
	v_add_f32_e32 v9, v14, v147
	s_waitcnt vmcnt(42)
	v_mul_f32_e32 v12, v5, v9
	v_mul_f32_e32 v14, v4, v9
	v_fma_f32 v12, v4, v8, -v12
	v_fma_f32 v14, v5, v8, v14
	v_add_f32_e32 v8, v12, v148
	v_add_f32_e32 v9, v14, v149
	s_waitcnt vmcnt(40)
	v_mul_f32_e32 v12, v5, v9
	v_mul_f32_e32 v14, v4, v9
	v_fma_f32 v12, v4, v8, -v12
	v_fma_f32 v14, v5, v8, v14
	v_add_f32_e32 v8, v12, v150
	v_add_f32_e32 v9, v14, v151
	s_waitcnt vmcnt(38)
	v_mul_f32_e32 v12, v5, v9
	v_mul_f32_e32 v14, v4, v9
	v_fma_f32 v12, v4, v8, -v12
	v_fma_f32 v14, v5, v8, v14
	v_add_f32_e32 v8, v12, v152
	v_add_f32_e32 v9, v14, v153
	s_waitcnt vmcnt(36)
	v_mul_f32_e32 v12, v5, v9
	v_mul_f32_e32 v14, v4, v9
	v_fma_f32 v12, v4, v8, -v12
	v_fma_f32 v14, v5, v8, v14
	v_add_f32_e32 v8, v12, v154
	v_add_f32_e32 v9, v14, v155
	s_waitcnt vmcnt(34)
	v_mul_f32_e32 v12, v5, v9
	v_mul_f32_e32 v14, v4, v9
	v_fma_f32 v12, v4, v8, -v12
	v_fma_f32 v14, v5, v8, v14
	v_add_f32_e32 v8, v12, v156
	v_add_f32_e32 v9, v14, v157
	s_waitcnt vmcnt(32)
	v_mul_f32_e32 v12, v5, v9
	v_mul_f32_e32 v14, v4, v9
	v_fma_f32 v12, v4, v8, -v12
	v_fma_f32 v14, v5, v8, v14
	v_add_f32_e32 v8, v12, v158
	v_add_f32_e32 v9, v14, v159
	s_waitcnt vmcnt(30)
	v_mul_f32_e32 v12, v5, v9
	v_mul_f32_e32 v14, v4, v9
	v_fma_f32 v12, v4, v8, -v12
	v_fma_f32 v14, v5, v8, v14
	v_add_f32_e32 v8, v12, v160
	v_add_f32_e32 v9, v14, v161
	s_waitcnt vmcnt(28)
	v_mul_f32_e32 v12, v5, v9
	v_mul_f32_e32 v14, v4, v9
	v_fma_f32 v12, v4, v8, -v12
	v_fma_f32 v14, v5, v8, v14
	v_add_f32_e32 v8, v12, v162
	v_add_f32_e32 v9, v14, v163
	s_waitcnt vmcnt(26)
	v_mul_f32_e32 v12, v5, v9
	v_mul_f32_e32 v14, v4, v9
	v_fma_f32 v12, v4, v8, -v12
	v_fma_f32 v14, v5, v8, v14
	v_add_f32_e32 v8, v12, v164
	v_add_f32_e32 v9, v14, v165
	s_waitcnt vmcnt(24)
	v_mul_f32_e32 v12, v5, v9
	v_mul_f32_e32 v14, v4, v9
	v_fma_f32 v12, v4, v8, -v12
	v_fma_f32 v14, v5, v8, v14
	v_add_f32_e32 v8, v12, v166
	v_add_f32_e32 v9, v14, v167
	s_waitcnt vmcnt(22)
; __device__ __forceinline__ f32x2 cmul(f32x2 a, f32x2 b) { return (f32x2){a.x * b.x - a.y * b.y, a.x * b.y + a.y * b.x}; }
; __global__ void __launch_bounds__(NTHR, 2) hymba_fwd(Params P) {
;     ...
;         for (int c = 0; c < 64; ++c) { const f32x2 s = {sp[c * 128 + n], sp[c * 128 + 64 + n]}; const f32x2 ax = cmul(a16, e); e = (f32x2){ax.x + s.x, ax.y + s.y}; }
;         EE[w * 64 + n] = e;
;         __syncthreads();
;         f32x2 a64 = a16;
; #pragma unroll
;         for (int i = 0; i < 6; ++i) a64 = cmul(a64, a64);
;         f32x2 h = {0.f, 0.f};
;         for (int ww = 0; ww < w; ++ww) { const f32x2 ax = cmul(a64, h); const f32x2 ev = EE[ww * 64 + n]; h = (f32x2){ax.x + ev.x, ax.y + ev.y}; }
	v_mul_f32_e32 v12, v5, v9
	v_mul_f32_e32 v14, v4, v9
	v_fma_f32 v12, v4, v8, -v12
	v_fma_f32 v14, v5, v8, v14
	v_add_f32_e32 v8, v12, v168
	v_add_f32_e32 v9, v14, v169
	s_waitcnt vmcnt(20)
	v_mul_f32_e32 v12, v5, v9
	v_mul_f32_e32 v14, v4, v9
	v_fma_f32 v12, v4, v8, -v12
	v_fma_f32 v14, v5, v8, v14
	v_add_f32_e32 v8, v12, v170
	v_add_f32_e32 v9, v14, v171
	s_waitcnt vmcnt(18)
	v_mul_f32_e32 v12, v5, v9
	v_mul_f32_e32 v14, v4, v9
	v_fma_f32 v12, v4, v8, -v12
	v_fma_f32 v14, v5, v8, v14
	v_add_f32_e32 v8, v12, v172
	v_add_f32_e32 v9, v14, v173
	s_waitcnt vmcnt(16)
	v_mul_f32_e32 v12, v5, v9
	v_mul_f32_e32 v14, v4, v9
	v_fma_f32 v12, v4, v8, -v12
	v_fma_f32 v14, v5, v8, v14
	v_add_f32_e32 v8, v12, v174
	v_add_f32_e32 v9, v14, v175
	s_waitcnt vmcnt(14)
	v_mul_f32_e32 v12, v5, v9
	v_mul_f32_e32 v14, v4, v9
	v_fma_f32 v12, v4, v8, -v12
	v_fma_f32 v14, v5, v8, v14
	v_add_f32_e32 v8, v12, v176
	v_add_f32_e32 v9, v14, v177
	s_waitcnt vmcnt(12)
	v_mul_f32_e32 v12, v5, v9
	v_mul_f32_e32 v14, v4, v9
	v_fma_f32 v12, v4, v8, -v12
	v_fma_f32 v14, v5, v8, v14
	v_add_f32_e32 v8, v12, v178
	v_add_f32_e32 v9, v14, v179
	s_waitcnt vmcnt(10)
	v_mul_f32_e32 v12, v5, v9
	v_mul_f32_e32 v14, v4, v9
	v_fma_f32 v12, v4, v8, -v12
	v_fma_f32 v14, v5, v8, v14
	v_add_f32_e32 v8, v12, v180
	v_add_f32_e32 v9, v14, v181
	s_waitcnt vmcnt(8)
	v_mul_f32_e32 v12, v5, v9
	v_mul_f32_e32 v14, v4, v9
	v_fma_f32 v12, v4, v8, -v12
	v_fma_f32 v14, v5, v8, v14
	v_add_f32_e32 v8, v12, v182
	v_add_f32_e32 v9, v14, v183
	s_waitcnt vmcnt(6)
	v_mul_f32_e32 v12, v5, v9
	v_mul_f32_e32 v14, v4, v9
	v_fma_f32 v12, v4, v8, -v12
	v_fma_f32 v14, v5, v8, v14
	v_add_f32_e32 v8, v12, v184
	v_add_f32_e32 v9, v14, v185
	s_waitcnt vmcnt(4)
	v_mul_f32_e32 v12, v5, v9
	v_mul_f32_e32 v14, v4, v9
	v_fma_f32 v12, v4, v8, -v12
	v_fma_f32 v14, v5, v8, v14
	v_add_f32_e32 v8, v12, v186
	v_add_f32_e32 v9, v14, v187
	s_waitcnt vmcnt(2)
	v_mul_f32_e32 v12, v5, v9
	v_mul_f32_e32 v14, v4, v9
	v_fma_f32 v12, v4, v8, -v12
	v_fma_f32 v14, v5, v8, v14
	v_add_f32_e32 v8, v12, v188
	v_add_f32_e32 v9, v14, v189
	s_waitcnt vmcnt(0)
	v_mul_f32_e32 v12, v5, v9
	v_mul_f32_e32 v14, v4, v9
	v_fma_f32 v12, v4, v8, -v12
	v_fma_f32 v14, v5, v8, v14
	v_add_f32_e32 v8, v12, v190
	v_add_f32_e32 v9, v14, v191
	ds_write_b64 v7, v[8:9]
	v_mov_b32_e32 v16, v4
	v_mov_b32_e32 v17, v5
	v_mul_f32_e32 v12, v17, v17
	v_mul_f32_e32 v14, v16, v17
	v_fma_f32 v12, v16, v16, -v12
	v_fma_f32 v17, v17, v16, v14
	v_mov_b32_e32 v16, v12
	v_mul_f32_e32 v12, v17, v17
	v_mul_f32_e32 v14, v16, v17
	v_fma_f32 v12, v16, v16, -v12
	v_fma_f32 v17, v17, v16, v14
	v_mov_b32_e32 v16, v12
	v_mul_f32_e32 v12, v17, v17
	v_mul_f32_e32 v14, v16, v17
	v_fma_f32 v12, v16, v16, -v12
	v_fma_f32 v17, v17, v16, v14
	v_mov_b32_e32 v16, v12
	v_mul_f32_e32 v12, v17, v17
	v_mul_f32_e32 v14, v16, v17
	v_fma_f32 v12, v16, v16, -v12
	v_fma_f32 v17, v17, v16, v14
	v_mov_b32_e32 v16, v12
	v_mul_f32_e32 v12, v17, v17
	v_mul_f32_e32 v14, v16, v17
	v_fma_f32 v12, v16, v16, -v12
	v_fma_f32 v17, v17, v16, v14
	v_mov_b32_e32 v16, v12
	v_mul_f32_e32 v12, v17, v17
	v_mul_f32_e32 v14, v16, v17
	v_fma_f32 v12, v16, v16, -v12
	v_fma_f32 v17, v17, v16, v14
	v_mov_b32_e32 v16, v12
	s_waitcnt lgkmcnt(0)
	s_barrier
	v_lshlrev_b32_e32 v18, 3, v2
	ds_read_b64 v[20:21], v18 offset:0
	ds_read_b64 v[22:23], v18 offset:512
	ds_read_b64 v[24:25], v18 offset:1024
	ds_read_b64 v[26:27], v18 offset:1536
	ds_read_b64 v[28:29], v18 offset:2048
	ds_read_b64 v[30:31], v18 offset:2560
	ds_read_b64 v[32:33], v18 offset:3072
	v_mov_b32_e32 v10, 0
	v_mov_b32_e32 v11, 0
	s_waitcnt lgkmcnt(0)
	s_cmp_le_u32 s12, 0
	s_cbranch_scc1 .Lmy_ch_hdone
	v_mul_f32_e32 v12, v17, v11
	v_mul_f32_e32 v14, v16, v11
	v_fma_f32 v12, v16, v10, -v12
	v_fma_f32 v14, v17, v10, v14
	v_add_f32_e32 v10, v12, v20
	v_add_f32_e32 v11, v14, v21
	s_cmp_le_u32 s12, 1
	s_cbranch_scc1 .Lmy_ch_hdone
	v_mul_f32_e32 v12, v17, v11
	v_mul_f32_e32 v14, v16, v11
	v_fma_f32 v12, v16, v10, -v12
	v_fma_f32 v14, v17, v10, v14
	v_add_f32_e32 v10, v12, v22
	v_add_f32_e32 v11, v14, v23
	s_cmp_le_u32 s12, 2
	s_cbranch_scc1 .Lmy_ch_hdone
	v_mul_f32_e32 v12, v17, v11
	v_mul_f32_e32 v14, v16, v11
	v_fma_f32 v12, v16, v10, -v12
	v_fma_f32 v14, v17, v10, v14
	v_add_f32_e32 v10, v12, v24
	v_add_f32_e32 v11, v14, v25
	s_cmp_le_u32 s12, 3
	s_cbranch_scc1 .Lmy_ch_hdone
	v_mul_f32_e32 v12, v17, v11
	v_mul_f32_e32 v14, v16, v11
	v_fma_f32 v12, v16, v10, -v12
	v_fma_f32 v14, v17, v10, v14
	v_add_f32_e32 v10, v12, v26
	v_add_f32_e32 v11, v14, v27
	s_cmp_le_u32 s12, 4
	s_cbranch_scc1 .Lmy_ch_hdone
	v_mul_f32_e32 v12, v17, v11
	v_mul_f32_e32 v14, v16, v11
	v_fma_f32 v12, v16, v10, -v12
	v_fma_f32 v14, v17, v10, v14
	v_add_f32_e32 v10, v12, v28
	v_add_f32_e32 v11, v14, v29
	s_cmp_le_u32 s12, 5
	s_cbranch_scc1 .Lmy_ch_hdone
	v_mul_f32_e32 v12, v17, v11
	v_mul_f32_e32 v14, v16, v11
	v_fma_f32 v12, v16, v10, -v12
	v_fma_f32 v14, v17, v10, v14
	v_add_f32_e32 v10, v12, v30
	v_add_f32_e32 v11, v14, v31
	s_cmp_le_u32 s12, 6
	s_cbranch_scc1 .Lmy_ch_hdone
	v_mul_f32_e32 v12, v17, v11
	v_mul_f32_e32 v14, v16, v11
	v_fma_f32 v12, v16, v10, -v12
	v_fma_f32 v14, v17, v10, v14
	v_add_f32_e32 v10, v12, v32
	v_add_f32_e32 v11, v14, v33
; __device__ __forceinline__ unsigned f2bf(float f) { unsigned u = __builtin_bit_cast(unsigned, f); return (u + 0x7fffu + ((u >> 16) & 1u)) >> 16; }
; __device__ __forceinline__ f32x2 cmul(f32x2 a, f32x2 b) { return (f32x2){a.x * b.x - a.y * b.y, a.x * b.y + a.y * b.x}; }
; __global__ void __launch_bounds__(NTHR, 2) hymba_fwd(Params P) {
;     ...
;         bf16_t* ux = UX + ((size_t)g * UXROWS + b * 512 + w * 64) * (UXR * 16);
; #pragma unroll 32
;         for (int c = 0; c < 64; ++c) {
;             ux[(c * UXR + 16) * 16 + n] = (bf16_t)f2bf(h.x); ux[(c * UXR + 20) * 16 + n] = (bf16_t)f2bf(h.y);
;             const f32x2 s = {sp[c * 128 + n], sp[c * 128 + 64 + n]}; const f32x2 ax = cmul(a16, h); h = (f32x2){ax.x + s.x, ax.y + s.y}; }
.Lmy_ch_hdone:
	v_bfe_u32 v19, v10, 16, 1
	v_bfe_u32 v36, v11, 16, 1
	v_add3_u32 v19, v10, v19, s35
	v_add3_u32 v36, v11, v36, s35
	global_store_short_d16_hi v6, v19, s[10:11]
	global_store_short_d16_hi v6, v36, s[10:11] offset:128
	v_add_u32_e32 v6, 0x300, v6
	v_mul_f32_e32 v12, v5, v11
	v_mul_f32_e32 v14, v4, v11
	v_fma_f32 v12, v4, v10, -v12
	v_fma_f32 v14, v5, v10, v14
	v_add_f32_e32 v10, v12, v64
	v_add_f32_e32 v11, v14, v65
	v_bfe_u32 v19, v10, 16, 1
	v_bfe_u32 v36, v11, 16, 1
	v_add3_u32 v19, v10, v19, s35
	v_add3_u32 v36, v11, v36, s35
	global_store_short_d16_hi v6, v19, s[10:11]
	global_store_short_d16_hi v6, v36, s[10:11] offset:128
	v_add_u32_e32 v6, 0x300, v6
	v_mul_f32_e32 v12, v5, v11
	v_mul_f32_e32 v14, v4, v11
	v_fma_f32 v12, v4, v10, -v12
	v_fma_f32 v14, v5, v10, v14
	v_add_f32_e32 v10, v12, v66
	v_add_f32_e32 v11, v14, v67
	v_bfe_u32 v19, v10, 16, 1
	v_bfe_u32 v36, v11, 16, 1
	v_add3_u32 v19, v10, v19, s35
	v_add3_u32 v36, v11, v36, s35
	global_store_short_d16_hi v6, v19, s[10:11]
	global_store_short_d16_hi v6, v36, s[10:11] offset:128
	v_add_u32_e32 v6, 0x300, v6
	v_mul_f32_e32 v12, v5, v11
	v_mul_f32_e32 v14, v4, v11
	v_fma_f32 v12, v4, v10, -v12
	v_fma_f32 v14, v5, v10, v14
	v_add_f32_e32 v10, v12, v68
	v_add_f32_e32 v11, v14, v69
	v_bfe_u32 v19, v10, 16, 1
	v_bfe_u32 v36, v11, 16, 1
	v_add3_u32 v19, v10, v19, s35
	v_add3_u32 v36, v11, v36, s35
	global_store_short_d16_hi v6, v19, s[10:11]
	global_store_short_d16_hi v6, v36, s[10:11] offset:128
	v_add_u32_e32 v6, 0x300, v6
	v_mul_f32_e32 v12, v5, v11
	v_mul_f32_e32 v14, v4, v11
	v_fma_f32 v12, v4, v10, -v12
	v_fma_f32 v14, v5, v10, v14
	v_add_f32_e32 v10, v12, v70
	v_add_f32_e32 v11, v14, v71
	v_bfe_u32 v19, v10, 16, 1
	v_bfe_u32 v36, v11, 16, 1
	v_add3_u32 v19, v10, v19, s35
	v_add3_u32 v36, v11, v36, s35
	global_store_short_d16_hi v6, v19, s[10:11]
	global_store_short_d16_hi v6, v36, s[10:11] offset:128
	v_add_u32_e32 v6, 0x300, v6
	v_mul_f32_e32 v12, v5, v11
	v_mul_f32_e32 v14, v4, v11
	v_fma_f32 v12, v4, v10, -v12
	v_fma_f32 v14, v5, v10, v14
	v_add_f32_e32 v10, v12, v72
	v_add_f32_e32 v11, v14, v73
	v_bfe_u32 v19, v10, 16, 1
	v_bfe_u32 v36, v11, 16, 1
	v_add3_u32 v19, v10, v19, s35
	v_add3_u32 v36, v11, v36, s35
	global_store_short_d16_hi v6, v19, s[10:11]
	global_store_short_d16_hi v6, v36, s[10:11] offset:128
	v_add_u32_e32 v6, 0x300, v6
	v_mul_f32_e32 v12, v5, v11
	v_mul_f32_e32 v14, v4, v11
	v_fma_f32 v12, v4, v10, -v12
	v_fma_f32 v14, v5, v10, v14
	v_add_f32_e32 v10, v12, v74
	v_add_f32_e32 v11, v14, v75
	v_bfe_u32 v19, v10, 16, 1
	v_bfe_u32 v36, v11, 16, 1
	v_add3_u32 v19, v10, v19, s35
	v_add3_u32 v36, v11, v36, s35
	global_store_short_d16_hi v6, v19, s[10:11]
	global_store_short_d16_hi v6, v36, s[10:11] offset:128
	v_add_u32_e32 v6, 0x300, v6
	v_mul_f32_e32 v12, v5, v11
	v_mul_f32_e32 v14, v4, v11
	v_fma_f32 v12, v4, v10, -v12
	v_fma_f32 v14, v5, v10, v14
	v_add_f32_e32 v10, v12, v76
	v_add_f32_e32 v11, v14, v77
	v_bfe_u32 v19, v10, 16, 1
	v_bfe_u32 v36, v11, 16, 1
	v_add3_u32 v19, v10, v19, s35
	v_add3_u32 v36, v11, v36, s35
	global_store_short_d16_hi v6, v19, s[10:11]
	global_store_short_d16_hi v6, v36, s[10:11] offset:128
	v_add_u32_e32 v6, 0x300, v6
	v_mul_f32_e32 v12, v5, v11
	v_mul_f32_e32 v14, v4, v11
	v_fma_f32 v12, v4, v10, -v12
	v_fma_f32 v14, v5, v10, v14
	v_add_f32_e32 v10, v12, v78
	v_add_f32_e32 v11, v14, v79
	v_bfe_u32 v19, v10, 16, 1
	v_bfe_u32 v36, v11, 16, 1
	v_add3_u32 v19, v10, v19, s35
	v_add3_u32 v36, v11, v36, s35
	global_store_short_d16_hi v6, v19, s[10:11]
	global_store_short_d16_hi v6, v36, s[10:11] offset:128
	v_add_u32_e32 v6, 0x300, v6
	v_mul_f32_e32 v12, v5, v11
	v_mul_f32_e32 v14, v4, v11
	v_fma_f32 v12, v4, v10, -v12
	v_fma_f32 v14, v5, v10, v14
	v_add_f32_e32 v10, v12, v80
	v_add_f32_e32 v11, v14, v81
	v_bfe_u32 v19, v10, 16, 1
	v_bfe_u32 v36, v11, 16, 1
	v_add3_u32 v19, v10, v19, s35
	v_add3_u32 v36, v11, v36, s35
	global_store_short_d16_hi v6, v19, s[10:11]
	global_store_short_d16_hi v6, v36, s[10:11] offset:128
	v_add_u32_e32 v6, 0x300, v6
	v_mul_f32_e32 v12, v5, v11
	v_mul_f32_e32 v14, v4, v11
	v_fma_f32 v12, v4, v10, -v12
	v_fma_f32 v14, v5, v10, v14
	v_add_f32_e32 v10, v12, v82
	v_add_f32_e32 v11, v14, v83
	v_bfe_u32 v19, v10, 16, 1
	v_bfe_u32 v36, v11, 16, 1
	v_add3_u32 v19, v10, v19, s35
	v_add3_u32 v36, v11, v36, s35
	global_store_short_d16_hi v6, v19, s[10:11]
	global_store_short_d16_hi v6, v36, s[10:11] offset:128
	v_add_u32_e32 v6, 0x300, v6
	v_mul_f32_e32 v12, v5, v11
	v_mul_f32_e32 v14, v4, v11
	v_fma_f32 v12, v4, v10, -v12
	v_fma_f32 v14, v5, v10, v14
	v_add_f32_e32 v10, v12, v84
	v_add_f32_e32 v11, v14, v85
	v_bfe_u32 v19, v10, 16, 1
	v_bfe_u32 v36, v11, 16, 1
	v_add3_u32 v19, v10, v19, s35
	v_add3_u32 v36, v11, v36, s35
	global_store_short_d16_hi v6, v19, s[10:11]
	global_store_short_d16_hi v6, v36, s[10:11] offset:128
	v_add_u32_e32 v6, 0x300, v6
	v_mul_f32_e32 v12, v5, v11
	v_mul_f32_e32 v14, v4, v11
	v_fma_f32 v12, v4, v10, -v12
	v_fma_f32 v14, v5, v10, v14
	v_add_f32_e32 v10, v12, v86
	v_add_f32_e32 v11, v14, v87
	v_bfe_u32 v19, v10, 16, 1
	v_bfe_u32 v36, v11, 16, 1
	v_add3_u32 v19, v10, v19, s35
	v_add3_u32 v36, v11, v36, s35
	global_store_short_d16_hi v6, v19, s[10:11]
	global_store_short_d16_hi v6, v36, s[10:11] offset:128
	v_add_u32_e32 v6, 0x300, v6
	v_mul_f32_e32 v12, v5, v11
	v_mul_f32_e32 v14, v4, v11
	v_fma_f32 v12, v4, v10, -v12
	v_fma_f32 v14, v5, v10, v14
	v_add_f32_e32 v10, v12, v88
	v_add_f32_e32 v11, v14, v89
	v_bfe_u32 v19, v10, 16, 1
	v_bfe_u32 v36, v11, 16, 1
	v_add3_u32 v19, v10, v19, s35
	v_add3_u32 v36, v11, v36, s35
	global_store_short_d16_hi v6, v19, s[10:11]
; __device__ __forceinline__ unsigned f2bf(float f) { unsigned u = __builtin_bit_cast(unsigned, f); return (u + 0x7fffu + ((u >> 16) & 1u)) >> 16; }
; __device__ __forceinline__ f32x2 cmul(f32x2 a, f32x2 b) { return (f32x2){a.x * b.x - a.y * b.y, a.x * b.y + a.y * b.x}; }
; __global__ void __launch_bounds__(NTHR, 2) hymba_fwd(Params P) {
;     ...
;         bf16_t* ux = UX + ((size_t)g * UXROWS + b * 512 + w * 64) * (UXR * 16);
; #pragma unroll 32
;         for (int c = 0; c < 64; ++c) {
;             ux[(c * UXR + 16) * 16 + n] = (bf16_t)f2bf(h.x); ux[(c * UXR + 20) * 16 + n] = (bf16_t)f2bf(h.y);
;             const f32x2 s = {sp[c * 128 + n], sp[c * 128 + 64 + n]}; const f32x2 ax = cmul(a16, h); h = (f32x2){ax.x + s.x, ax.y + s.y}; }
	global_store_short_d16_hi v6, v36, s[10:11] offset:128
	v_add_u32_e32 v6, 0x300, v6
	v_mul_f32_e32 v12, v5, v11
	v_mul_f32_e32 v14, v4, v11
	v_fma_f32 v12, v4, v10, -v12
	v_fma_f32 v14, v5, v10, v14
	v_add_f32_e32 v10, v12, v90
	v_add_f32_e32 v11, v14, v91
	v_bfe_u32 v19, v10, 16, 1
	v_bfe_u32 v36, v11, 16, 1
	v_add3_u32 v19, v10, v19, s35
	v_add3_u32 v36, v11, v36, s35
	global_store_short_d16_hi v6, v19, s[10:11]
	global_store_short_d16_hi v6, v36, s[10:11] offset:128
	v_add_u32_e32 v6, 0x300, v6
	v_mul_f32_e32 v12, v5, v11
	v_mul_f32_e32 v14, v4, v11
	v_fma_f32 v12, v4, v10, -v12
	v_fma_f32 v14, v5, v10, v14
	v_add_f32_e32 v10, v12, v92
	v_add_f32_e32 v11, v14, v93
	v_bfe_u32 v19, v10, 16, 1
	v_bfe_u32 v36, v11, 16, 1
	v_add3_u32 v19, v10, v19, s35
	v_add3_u32 v36, v11, v36, s35
	global_store_short_d16_hi v6, v19, s[10:11]
	global_store_short_d16_hi v6, v36, s[10:11] offset:128
	v_add_u32_e32 v6, 0x300, v6
	v_mul_f32_e32 v12, v5, v11
	v_mul_f32_e32 v14, v4, v11
	v_fma_f32 v12, v4, v10, -v12
	v_fma_f32 v14, v5, v10, v14
	v_add_f32_e32 v10, v12, v94
	v_add_f32_e32 v11, v14, v95
	v_bfe_u32 v19, v10, 16, 1
	v_bfe_u32 v36, v11, 16, 1
	v_add3_u32 v19, v10, v19, s35
	v_add3_u32 v36, v11, v36, s35
	global_store_short_d16_hi v6, v19, s[10:11]
	global_store_short_d16_hi v6, v36, s[10:11] offset:128
	v_add_u32_e32 v6, 0x300, v6
	v_mul_f32_e32 v12, v5, v11
	v_mul_f32_e32 v14, v4, v11
	v_fma_f32 v12, v4, v10, -v12
	v_fma_f32 v14, v5, v10, v14
	v_add_f32_e32 v10, v12, v96
	v_add_f32_e32 v11, v14, v97
	v_bfe_u32 v19, v10, 16, 1
	v_bfe_u32 v36, v11, 16, 1
	v_add3_u32 v19, v10, v19, s35
	v_add3_u32 v36, v11, v36, s35
	global_store_short_d16_hi v6, v19, s[10:11]
	global_store_short_d16_hi v6, v36, s[10:11] offset:128
	v_add_u32_e32 v6, 0x300, v6
	v_mul_f32_e32 v12, v5, v11
	v_mul_f32_e32 v14, v4, v11
	v_fma_f32 v12, v4, v10, -v12
	v_fma_f32 v14, v5, v10, v14
	v_add_f32_e32 v10, v12, v98
	v_add_f32_e32 v11, v14, v99
	v_bfe_u32 v19, v10, 16, 1
	v_bfe_u32 v36, v11, 16, 1
	v_add3_u32 v19, v10, v19, s35
	v_add3_u32 v36, v11, v36, s35
	global_store_short_d16_hi v6, v19, s[10:11]
	global_store_short_d16_hi v6, v36, s[10:11] offset:128
	v_add_u32_e32 v6, 0x300, v6
	v_mul_f32_e32 v12, v5, v11
	v_mul_f32_e32 v14, v4, v11
	v_fma_f32 v12, v4, v10, -v12
	v_fma_f32 v14, v5, v10, v14
	v_add_f32_e32 v10, v12, v100
	v_add_f32_e32 v11, v14, v101
	v_bfe_u32 v19, v10, 16, 1
	v_bfe_u32 v36, v11, 16, 1
	v_add3_u32 v19, v10, v19, s35
	v_add3_u32 v36, v11, v36, s35
	global_store_short_d16_hi v6, v19, s[10:11]
	global_store_short_d16_hi v6, v36, s[10:11] offset:128
	v_add_u32_e32 v6, 0x300, v6
	v_mul_f32_e32 v12, v5, v11
	v_mul_f32_e32 v14, v4, v11
	v_fma_f32 v12, v4, v10, -v12
	v_fma_f32 v14, v5, v10, v14
	v_add_f32_e32 v10, v12, v102
	v_add_f32_e32 v11, v14, v103
	v_bfe_u32 v19, v10, 16, 1
	v_bfe_u32 v36, v11, 16, 1
	v_add3_u32 v19, v10, v19, s35
	v_add3_u32 v36, v11, v36, s35
	global_store_short_d16_hi v6, v19, s[10:11]
	global_store_short_d16_hi v6, v36, s[10:11] offset:128
	v_add_u32_e32 v6, 0x300, v6
	v_mul_f32_e32 v12, v5, v11
	v_mul_f32_e32 v14, v4, v11
	v_fma_f32 v12, v4, v10, -v12
	v_fma_f32 v14, v5, v10, v14
	v_add_f32_e32 v10, v12, v104
	v_add_f32_e32 v11, v14, v105
	v_bfe_u32 v19, v10, 16, 1
	v_bfe_u32 v36, v11, 16, 1
	v_add3_u32 v19, v10, v19, s35
	v_add3_u32 v36, v11, v36, s35
	global_store_short_d16_hi v6, v19, s[10:11]
	global_store_short_d16_hi v6, v36, s[10:11] offset:128
	v_add_u32_e32 v6, 0x300, v6
	v_mul_f32_e32 v12, v5, v11
	v_mul_f32_e32 v14, v4, v11
	v_fma_f32 v12, v4, v10, -v12
	v_fma_f32 v14, v5, v10, v14
	v_add_f32_e32 v10, v12, v106
	v_add_f32_e32 v11, v14, v107
	v_bfe_u32 v19, v10, 16, 1
	v_bfe_u32 v36, v11, 16, 1
	v_add3_u32 v19, v10, v19, s35
	v_add3_u32 v36, v11, v36, s35
	global_store_short_d16_hi v6, v19, s[10:11]
	global_store_short_d16_hi v6, v36, s[10:11] offset:128
	v_add_u32_e32 v6, 0x300, v6
	v_mul_f32_e32 v12, v5, v11
	v_mul_f32_e32 v14, v4, v11
	v_fma_f32 v12, v4, v10, -v12
	v_fma_f32 v14, v5, v10, v14
	v_add_f32_e32 v10, v12, v108
	v_add_f32_e32 v11, v14, v109
	v_bfe_u32 v19, v10, 16, 1
	v_bfe_u32 v36, v11, 16, 1
	v_add3_u32 v19, v10, v19, s35
	v_add3_u32 v36, v11, v36, s35
	global_store_short_d16_hi v6, v19, s[10:11]
	global_store_short_d16_hi v6, v36, s[10:11] offset:128
	v_add_u32_e32 v6, 0x300, v6
	v_mul_f32_e32 v12, v5, v11
	v_mul_f32_e32 v14, v4, v11
	v_fma_f32 v12, v4, v10, -v12
	v_fma_f32 v14, v5, v10, v14
	v_add_f32_e32 v10, v12, v110
	v_add_f32_e32 v11, v14, v111
	v_bfe_u32 v19, v10, 16, 1
	v_bfe_u32 v36, v11, 16, 1
	v_add3_u32 v19, v10, v19, s35
	v_add3_u32 v36, v11, v36, s35
	global_store_short_d16_hi v6, v19, s[10:11]
	global_store_short_d16_hi v6, v36, s[10:11] offset:128
	v_add_u32_e32 v6, 0x300, v6
	v_mul_f32_e32 v12, v5, v11
	v_mul_f32_e32 v14, v4, v11
	v_fma_f32 v12, v4, v10, -v12
	v_fma_f32 v14, v5, v10, v14
	v_add_f32_e32 v10, v12, v112
	v_add_f32_e32 v11, v14, v113
	v_bfe_u32 v19, v10, 16, 1
	v_bfe_u32 v36, v11, 16, 1
	v_add3_u32 v19, v10, v19, s35
	v_add3_u32 v36, v11, v36, s35
	global_store_short_d16_hi v6, v19, s[10:11]
	global_store_short_d16_hi v6, v36, s[10:11] offset:128
	v_add_u32_e32 v6, 0x300, v6
	v_mul_f32_e32 v12, v5, v11
	v_mul_f32_e32 v14, v4, v11
	v_fma_f32 v12, v4, v10, -v12
	v_fma_f32 v14, v5, v10, v14
	v_add_f32_e32 v10, v12, v114
	v_add_f32_e32 v11, v14, v115
	v_bfe_u32 v19, v10, 16, 1
	v_bfe_u32 v36, v11, 16, 1
	v_add3_u32 v19, v10, v19, s35
	v_add3_u32 v36, v11, v36, s35
	global_store_short_d16_hi v6, v19, s[10:11]
	global_store_short_d16_hi v6, v36, s[10:11] offset:128
	v_add_u32_e32 v6, 0x300, v6
	v_mul_f32_e32 v12, v5, v11
	v_mul_f32_e32 v14, v4, v11
	v_fma_f32 v12, v4, v10, -v12
; __device__ __forceinline__ unsigned f2bf(float f) { unsigned u = __builtin_bit_cast(unsigned, f); return (u + 0x7fffu + ((u >> 16) & 1u)) >> 16; }
; __device__ __forceinline__ f32x2 cmul(f32x2 a, f32x2 b) { return (f32x2){a.x * b.x - a.y * b.y, a.x * b.y + a.y * b.x}; }
; __global__ void __launch_bounds__(NTHR, 2) hymba_fwd(Params P) {
;     ...
;         bf16_t* ux = UX + ((size_t)g * UXROWS + b * 512 + w * 64) * (UXR * 16);
; #pragma unroll 32
;         for (int c = 0; c < 64; ++c) {
;             ux[(c * UXR + 16) * 16 + n] = (bf16_t)f2bf(h.x); ux[(c * UXR + 20) * 16 + n] = (bf16_t)f2bf(h.y);
;             const f32x2 s = {sp[c * 128 + n], sp[c * 128 + 64 + n]}; const f32x2 ax = cmul(a16, h); h = (f32x2){ax.x + s.x, ax.y + s.y}; }
	v_fma_f32 v14, v5, v10, v14
	v_add_f32_e32 v10, v12, v116
	v_add_f32_e32 v11, v14, v117
	v_bfe_u32 v19, v10, 16, 1
	v_bfe_u32 v36, v11, 16, 1
	v_add3_u32 v19, v10, v19, s35
	v_add3_u32 v36, v11, v36, s35
	global_store_short_d16_hi v6, v19, s[10:11]
	global_store_short_d16_hi v6, v36, s[10:11] offset:128
	v_add_u32_e32 v6, 0x300, v6
	v_mul_f32_e32 v12, v5, v11
	v_mul_f32_e32 v14, v4, v11
	v_fma_f32 v12, v4, v10, -v12
	v_fma_f32 v14, v5, v10, v14
	v_add_f32_e32 v10, v12, v118
	v_add_f32_e32 v11, v14, v119
	v_bfe_u32 v19, v10, 16, 1
	v_bfe_u32 v36, v11, 16, 1
	v_add3_u32 v19, v10, v19, s35
	v_add3_u32 v36, v11, v36, s35
	global_store_short_d16_hi v6, v19, s[10:11]
	global_store_short_d16_hi v6, v36, s[10:11] offset:128
	v_add_u32_e32 v6, 0x300, v6
	v_mul_f32_e32 v12, v5, v11
	v_mul_f32_e32 v14, v4, v11
	v_fma_f32 v12, v4, v10, -v12
	v_fma_f32 v14, v5, v10, v14
	v_add_f32_e32 v10, v12, v120
	v_add_f32_e32 v11, v14, v121
	v_bfe_u32 v19, v10, 16, 1
	v_bfe_u32 v36, v11, 16, 1
	v_add3_u32 v19, v10, v19, s35
	v_add3_u32 v36, v11, v36, s35
	global_store_short_d16_hi v6, v19, s[10:11]
	global_store_short_d16_hi v6, v36, s[10:11] offset:128
	v_add_u32_e32 v6, 0x300, v6
	v_mul_f32_e32 v12, v5, v11
	v_mul_f32_e32 v14, v4, v11
	v_fma_f32 v12, v4, v10, -v12
	v_fma_f32 v14, v5, v10, v14
	v_add_f32_e32 v10, v12, v122
	v_add_f32_e32 v11, v14, v123
	v_bfe_u32 v19, v10, 16, 1
	v_bfe_u32 v36, v11, 16, 1
	v_add3_u32 v19, v10, v19, s35
	v_add3_u32 v36, v11, v36, s35
	global_store_short_d16_hi v6, v19, s[10:11]
	global_store_short_d16_hi v6, v36, s[10:11] offset:128
	v_add_u32_e32 v6, 0x300, v6
	v_mul_f32_e32 v12, v5, v11
	v_mul_f32_e32 v14, v4, v11
	v_fma_f32 v12, v4, v10, -v12
	v_fma_f32 v14, v5, v10, v14
	v_add_f32_e32 v10, v12, v124
	v_add_f32_e32 v11, v14, v125
	v_bfe_u32 v19, v10, 16, 1
	v_bfe_u32 v36, v11, 16, 1
	v_add3_u32 v19, v10, v19, s35
	v_add3_u32 v36, v11, v36, s35
	global_store_short_d16_hi v6, v19, s[10:11]
	global_store_short_d16_hi v6, v36, s[10:11] offset:128
	v_add_u32_e32 v6, 0x300, v6
	v_mul_f32_e32 v12, v5, v11
	v_mul_f32_e32 v14, v4, v11
	v_fma_f32 v12, v4, v10, -v12
	v_fma_f32 v14, v5, v10, v14
	v_add_f32_e32 v10, v12, v126
	v_add_f32_e32 v11, v14, v127
	v_bfe_u32 v19, v10, 16, 1
	v_bfe_u32 v36, v11, 16, 1
	v_add3_u32 v19, v10, v19, s35
	v_add3_u32 v36, v11, v36, s35
	global_store_short_d16_hi v6, v19, s[10:11]
	global_store_short_d16_hi v6, v36, s[10:11] offset:128
	v_add_u32_e32 v6, 0x300, v6
	v_mul_f32_e32 v12, v5, v11
	v_mul_f32_e32 v14, v4, v11
	v_fma_f32 v12, v4, v10, -v12
	v_fma_f32 v14, v5, v10, v14
	v_add_f32_e32 v10, v12, v128
	v_add_f32_e32 v11, v14, v129
	v_bfe_u32 v19, v10, 16, 1
	v_bfe_u32 v36, v11, 16, 1
	v_add3_u32 v19, v10, v19, s35
	v_add3_u32 v36, v11, v36, s35
	global_store_short_d16_hi v6, v19, s[10:11]
	global_store_short_d16_hi v6, v36, s[10:11] offset:128
	v_add_u32_e32 v6, 0x300, v6
	v_mul_f32_e32 v12, v5, v11
	v_mul_f32_e32 v14, v4, v11
	v_fma_f32 v12, v4, v10, -v12
	v_fma_f32 v14, v5, v10, v14
	v_add_f32_e32 v10, v12, v130
	v_add_f32_e32 v11, v14, v131
	v_bfe_u32 v19, v10, 16, 1
	v_bfe_u32 v36, v11, 16, 1
	v_add3_u32 v19, v10, v19, s35
	v_add3_u32 v36, v11, v36, s35
	global_store_short_d16_hi v6, v19, s[10:11]
	global_store_short_d16_hi v6, v36, s[10:11] offset:128
	v_add_u32_e32 v6, 0x300, v6
	v_mul_f32_e32 v12, v5, v11
	v_mul_f32_e32 v14, v4, v11
	v_fma_f32 v12, v4, v10, -v12
	v_fma_f32 v14, v5, v10, v14
	v_add_f32_e32 v10, v12, v132
	v_add_f32_e32 v11, v14, v133
	v_bfe_u32 v19, v10, 16, 1
	v_bfe_u32 v36, v11, 16, 1
	v_add3_u32 v19, v10, v19, s35
	v_add3_u32 v36, v11, v36, s35
	global_store_short_d16_hi v6, v19, s[10:11]
	global_store_short_d16_hi v6, v36, s[10:11] offset:128
	v_add_u32_e32 v6, 0x300, v6
	v_mul_f32_e32 v12, v5, v11
	v_mul_f32_e32 v14, v4, v11
	v_fma_f32 v12, v4, v10, -v12
	v_fma_f32 v14, v5, v10, v14
	v_add_f32_e32 v10, v12, v134
	v_add_f32_e32 v11, v14, v135
	v_bfe_u32 v19, v10, 16, 1
	v_bfe_u32 v36, v11, 16, 1
	v_add3_u32 v19, v10, v19, s35
	v_add3_u32 v36, v11, v36, s35
	global_store_short_d16_hi v6, v19, s[10:11]
	global_store_short_d16_hi v6, v36, s[10:11] offset:128
	v_add_u32_e32 v6, 0x300, v6
	v_mul_f32_e32 v12, v5, v11
	v_mul_f32_e32 v14, v4, v11
	v_fma_f32 v12, v4, v10, -v12
	v_fma_f32 v14, v5, v10, v14
	v_add_f32_e32 v10, v12, v136
	v_add_f32_e32 v11, v14, v137
	v_bfe_u32 v19, v10, 16, 1
	v_bfe_u32 v36, v11, 16, 1
	v_add3_u32 v19, v10, v19, s35
	v_add3_u32 v36, v11, v36, s35
	global_store_short_d16_hi v6, v19, s[10:11]
	global_store_short_d16_hi v6, v36, s[10:11] offset:128
	v_add_u32_e32 v6, 0x300, v6
	v_mul_f32_e32 v12, v5, v11
	v_mul_f32_e32 v14, v4, v11
	v_fma_f32 v12, v4, v10, -v12
	v_fma_f32 v14, v5, v10, v14
	v_add_f32_e32 v10, v12, v138
	v_add_f32_e32 v11, v14, v139
	v_bfe_u32 v19, v10, 16, 1
	v_bfe_u32 v36, v11, 16, 1
	v_add3_u32 v19, v10, v19, s35
	v_add3_u32 v36, v11, v36, s35
	global_store_short_d16_hi v6, v19, s[10:11]
	global_store_short_d16_hi v6, v36, s[10:11] offset:128
	v_add_u32_e32 v6, 0x300, v6
	v_mul_f32_e32 v12, v5, v11
	v_mul_f32_e32 v14, v4, v11
	v_fma_f32 v12, v4, v10, -v12
	v_fma_f32 v14, v5, v10, v14
	v_add_f32_e32 v10, v12, v140
	v_add_f32_e32 v11, v14, v141
	v_bfe_u32 v19, v10, 16, 1
	v_bfe_u32 v36, v11, 16, 1
	v_add3_u32 v19, v10, v19, s35
	v_add3_u32 v36, v11, v36, s35
	global_store_short_d16_hi v6, v19, s[10:11]
	global_store_short_d16_hi v6, v36, s[10:11] offset:128
	v_add_u32_e32 v6, 0x300, v6
	v_mul_f32_e32 v12, v5, v11
	v_mul_f32_e32 v14, v4, v11
	v_fma_f32 v12, v4, v10, -v12
	v_fma_f32 v14, v5, v10, v14
	v_add_f32_e32 v10, v12, v142
	v_add_f32_e32 v11, v14, v143
	v_bfe_u32 v19, v10, 16, 1
	v_bfe_u32 v36, v11, 16, 1
	v_add3_u32 v19, v10, v19, s35
; __device__ __forceinline__ unsigned f2bf(float f) { unsigned u = __builtin_bit_cast(unsigned, f); return (u + 0x7fffu + ((u >> 16) & 1u)) >> 16; }
; __device__ __forceinline__ f32x2 cmul(f32x2 a, f32x2 b) { return (f32x2){a.x * b.x - a.y * b.y, a.x * b.y + a.y * b.x}; }
; __global__ void __launch_bounds__(NTHR, 2) hymba_fwd(Params P) {
;     ...
;         bf16_t* ux = UX + ((size_t)g * UXROWS + b * 512 + w * 64) * (UXR * 16);
; #pragma unroll 32
;         for (int c = 0; c < 64; ++c) {
;             ux[(c * UXR + 16) * 16 + n] = (bf16_t)f2bf(h.x); ux[(c * UXR + 20) * 16 + n] = (bf16_t)f2bf(h.y);
;             const f32x2 s = {sp[c * 128 + n], sp[c * 128 + 64 + n]}; const f32x2 ax = cmul(a16, h); h = (f32x2){ax.x + s.x, ax.y + s.y}; }
	v_add3_u32 v36, v11, v36, s35
	global_store_short_d16_hi v6, v19, s[10:11]
	global_store_short_d16_hi v6, v36, s[10:11] offset:128
	v_add_u32_e32 v6, 0x300, v6
	v_mul_f32_e32 v12, v5, v11
	v_mul_f32_e32 v14, v4, v11
	v_fma_f32 v12, v4, v10, -v12
	v_fma_f32 v14, v5, v10, v14
	v_add_f32_e32 v10, v12, v144
	v_add_f32_e32 v11, v14, v145
	v_bfe_u32 v19, v10, 16, 1
	v_bfe_u32 v36, v11, 16, 1
	v_add3_u32 v19, v10, v19, s35
	v_add3_u32 v36, v11, v36, s35
	global_store_short_d16_hi v6, v19, s[10:11]
	global_store_short_d16_hi v6, v36, s[10:11] offset:128
	v_add_u32_e32 v6, 0x300, v6
	v_mul_f32_e32 v12, v5, v11
	v_mul_f32_e32 v14, v4, v11
	v_fma_f32 v12, v4, v10, -v12
	v_fma_f32 v14, v5, v10, v14
	v_add_f32_e32 v10, v12, v146
	v_add_f32_e32 v11, v14, v147
	v_bfe_u32 v19, v10, 16, 1
	v_bfe_u32 v36, v11, 16, 1
	v_add3_u32 v19, v10, v19, s35
	v_add3_u32 v36, v11, v36, s35
	global_store_short_d16_hi v6, v19, s[10:11]
	global_store_short_d16_hi v6, v36, s[10:11] offset:128
	v_add_u32_e32 v6, 0x300, v6
	v_mul_f32_e32 v12, v5, v11
	v_mul_f32_e32 v14, v4, v11
	v_fma_f32 v12, v4, v10, -v12
	v_fma_f32 v14, v5, v10, v14
	v_add_f32_e32 v10, v12, v148
	v_add_f32_e32 v11, v14, v149
	v_bfe_u32 v19, v10, 16, 1
	v_bfe_u32 v36, v11, 16, 1
	v_add3_u32 v19, v10, v19, s35
	v_add3_u32 v36, v11, v36, s35
	global_store_short_d16_hi v6, v19, s[10:11]
	global_store_short_d16_hi v6, v36, s[10:11] offset:128
	v_add_u32_e32 v6, 0x300, v6
	v_mul_f32_e32 v12, v5, v11
	v_mul_f32_e32 v14, v4, v11
	v_fma_f32 v12, v4, v10, -v12
	v_fma_f32 v14, v5, v10, v14
	v_add_f32_e32 v10, v12, v150
	v_add_f32_e32 v11, v14, v151
	v_bfe_u32 v19, v10, 16, 1
	v_bfe_u32 v36, v11, 16, 1
	v_add3_u32 v19, v10, v19, s35
	v_add3_u32 v36, v11, v36, s35
	global_store_short_d16_hi v6, v19, s[10:11]
	global_store_short_d16_hi v6, v36, s[10:11] offset:128
	v_add_u32_e32 v6, 0x300, v6
	v_mul_f32_e32 v12, v5, v11
	v_mul_f32_e32 v14, v4, v11
	v_fma_f32 v12, v4, v10, -v12
	v_fma_f32 v14, v5, v10, v14
	v_add_f32_e32 v10, v12, v152
	v_add_f32_e32 v11, v14, v153
	v_bfe_u32 v19, v10, 16, 1
	v_bfe_u32 v36, v11, 16, 1
	v_add3_u32 v19, v10, v19, s35
	v_add3_u32 v36, v11, v36, s35
	global_store_short_d16_hi v6, v19, s[10:11]
	global_store_short_d16_hi v6, v36, s[10:11] offset:128
	v_add_u32_e32 v6, 0x300, v6
	v_mul_f32_e32 v12, v5, v11
	v_mul_f32_e32 v14, v4, v11
	v_fma_f32 v12, v4, v10, -v12
	v_fma_f32 v14, v5, v10, v14
	v_add_f32_e32 v10, v12, v154
	v_add_f32_e32 v11, v14, v155
	v_bfe_u32 v19, v10, 16, 1
	v_bfe_u32 v36, v11, 16, 1
	v_add3_u32 v19, v10, v19, s35
	v_add3_u32 v36, v11, v36, s35
	global_store_short_d16_hi v6, v19, s[10:11]
	global_store_short_d16_hi v6, v36, s[10:11] offset:128
	v_add_u32_e32 v6, 0x300, v6
	v_mul_f32_e32 v12, v5, v11
	v_mul_f32_e32 v14, v4, v11
	v_fma_f32 v12, v4, v10, -v12
	v_fma_f32 v14, v5, v10, v14
	v_add_f32_e32 v10, v12, v156
	v_add_f32_e32 v11, v14, v157
	v_bfe_u32 v19, v10, 16, 1
	v_bfe_u32 v36, v11, 16, 1
	v_add3_u32 v19, v10, v19, s35
	v_add3_u32 v36, v11, v36, s35
	global_store_short_d16_hi v6, v19, s[10:11]
	global_store_short_d16_hi v6, v36, s[10:11] offset:128
	v_add_u32_e32 v6, 0x300, v6
	v_mul_f32_e32 v12, v5, v11
	v_mul_f32_e32 v14, v4, v11
	v_fma_f32 v12, v4, v10, -v12
	v_fma_f32 v14, v5, v10, v14
	v_add_f32_e32 v10, v12, v158
	v_add_f32_e32 v11, v14, v159
	v_bfe_u32 v19, v10, 16, 1
	v_bfe_u32 v36, v11, 16, 1
	v_add3_u32 v19, v10, v19, s35
	v_add3_u32 v36, v11, v36, s35
	global_store_short_d16_hi v6, v19, s[10:11]
	global_store_short_d16_hi v6, v36, s[10:11] offset:128
	v_add_u32_e32 v6, 0x300, v6
	v_mul_f32_e32 v12, v5, v11
	v_mul_f32_e32 v14, v4, v11
	v_fma_f32 v12, v4, v10, -v12
	v_fma_f32 v14, v5, v10, v14
	v_add_f32_e32 v10, v12, v160
	v_add_f32_e32 v11, v14, v161
	v_bfe_u32 v19, v10, 16, 1
	v_bfe_u32 v36, v11, 16, 1
	v_add3_u32 v19, v10, v19, s35
	v_add3_u32 v36, v11, v36, s35
	global_store_short_d16_hi v6, v19, s[10:11]
	global_store_short_d16_hi v6, v36, s[10:11] offset:128
	v_add_u32_e32 v6, 0x300, v6
	v_mul_f32_e32 v12, v5, v11
	v_mul_f32_e32 v14, v4, v11
	v_fma_f32 v12, v4, v10, -v12
	v_fma_f32 v14, v5, v10, v14
	v_add_f32_e32 v10, v12, v162
	v_add_f32_e32 v11, v14, v163
	v_bfe_u32 v19, v10, 16, 1
	v_bfe_u32 v36, v11, 16, 1
	v_add3_u32 v19, v10, v19, s35
	v_add3_u32 v36, v11, v36, s35
	global_store_short_d16_hi v6, v19, s[10:11]
	global_store_short_d16_hi v6, v36, s[10:11] offset:128
	v_add_u32_e32 v6, 0x300, v6
	v_mul_f32_e32 v12, v5, v11
	v_mul_f32_e32 v14, v4, v11
	v_fma_f32 v12, v4, v10, -v12
	v_fma_f32 v14, v5, v10, v14
	v_add_f32_e32 v10, v12, v164
	v_add_f32_e32 v11, v14, v165
	v_bfe_u32 v19, v10, 16, 1
	v_bfe_u32 v36, v11, 16, 1
	v_add3_u32 v19, v10, v19, s35
	v_add3_u32 v36, v11, v36, s35
	global_store_short_d16_hi v6, v19, s[10:11]
	global_store_short_d16_hi v6, v36, s[10:11] offset:128
	v_add_u32_e32 v6, 0x300, v6
	v_mul_f32_e32 v12, v5, v11
	v_mul_f32_e32 v14, v4, v11
	v_fma_f32 v12, v4, v10, -v12
	v_fma_f32 v14, v5, v10, v14
	v_add_f32_e32 v10, v12, v166
	v_add_f32_e32 v11, v14, v167
	v_bfe_u32 v19, v10, 16, 1
	v_bfe_u32 v36, v11, 16, 1
	v_add3_u32 v19, v10, v19, s35
	v_add3_u32 v36, v11, v36, s35
	global_store_short_d16_hi v6, v19, s[10:11]
	global_store_short_d16_hi v6, v36, s[10:11] offset:128
; __device__ __forceinline__ unsigned f2bf(float f) { unsigned u = __builtin_bit_cast(unsigned, f); return (u + 0x7fffu + ((u >> 16) & 1u)) >> 16; }
; __device__ __forceinline__ f32x2 cmul(f32x2 a, f32x2 b) { return (f32x2){a.x * b.x - a.y * b.y, a.x * b.y + a.y * b.x}; }
; __global__ void __launch_bounds__(NTHR, 2) hymba_fwd(Params P) {
;     ...
;         bf16_t* ux = UX + ((size_t)g * UXROWS + b * 512 + w * 64) * (UXR * 16);
; #pragma unroll 32
;         for (int c = 0; c < 64; ++c) {
;             ux[(c * UXR + 16) * 16 + n] = (bf16_t)f2bf(h.x); ux[(c * UXR + 20) * 16 + n] = (bf16_t)f2bf(h.y);
;             const f32x2 s = {sp[c * 128 + n], sp[c * 128 + 64 + n]}; const f32x2 ax = cmul(a16, h); h = (f32x2){ax.x + s.x, ax.y + s.y}; }
;         if (w == 7) { out[O_RP + (b * NG + g) * 64 + n] = h.x; out[O_IP + (b * NG + g) * 64 + n] = h.y; }
;         __syncthreads();
	v_add_u32_e32 v6, 0x300, v6
	v_mul_f32_e32 v12, v5, v11
	v_mul_f32_e32 v14, v4, v11
	v_fma_f32 v12, v4, v10, -v12
	v_fma_f32 v14, v5, v10, v14
	v_add_f32_e32 v10, v12, v168
	v_add_f32_e32 v11, v14, v169
	v_bfe_u32 v19, v10, 16, 1
	v_bfe_u32 v36, v11, 16, 1
	v_add3_u32 v19, v10, v19, s35
	v_add3_u32 v36, v11, v36, s35
	global_store_short_d16_hi v6, v19, s[10:11]
	global_store_short_d16_hi v6, v36, s[10:11] offset:128
	v_add_u32_e32 v6, 0x300, v6
	v_mul_f32_e32 v12, v5, v11
	v_mul_f32_e32 v14, v4, v11
	v_fma_f32 v12, v4, v10, -v12
	v_fma_f32 v14, v5, v10, v14
	v_add_f32_e32 v10, v12, v170
	v_add_f32_e32 v11, v14, v171
	v_bfe_u32 v19, v10, 16, 1
	v_bfe_u32 v36, v11, 16, 1
	v_add3_u32 v19, v10, v19, s35
	v_add3_u32 v36, v11, v36, s35
	global_store_short_d16_hi v6, v19, s[10:11]
	global_store_short_d16_hi v6, v36, s[10:11] offset:128
	v_add_u32_e32 v6, 0x300, v6
	v_mul_f32_e32 v12, v5, v11
	v_mul_f32_e32 v14, v4, v11
	v_fma_f32 v12, v4, v10, -v12
	v_fma_f32 v14, v5, v10, v14
	v_add_f32_e32 v10, v12, v172
	v_add_f32_e32 v11, v14, v173
	v_bfe_u32 v19, v10, 16, 1
	v_bfe_u32 v36, v11, 16, 1
	v_add3_u32 v19, v10, v19, s35
	v_add3_u32 v36, v11, v36, s35
	global_store_short_d16_hi v6, v19, s[10:11]
	global_store_short_d16_hi v6, v36, s[10:11] offset:128
	v_add_u32_e32 v6, 0x300, v6
	v_mul_f32_e32 v12, v5, v11
	v_mul_f32_e32 v14, v4, v11
	v_fma_f32 v12, v4, v10, -v12
	v_fma_f32 v14, v5, v10, v14
	v_add_f32_e32 v10, v12, v174
	v_add_f32_e32 v11, v14, v175
	v_bfe_u32 v19, v10, 16, 1
	v_bfe_u32 v36, v11, 16, 1
	v_add3_u32 v19, v10, v19, s35
	v_add3_u32 v36, v11, v36, s35
	global_store_short_d16_hi v6, v19, s[10:11]
	global_store_short_d16_hi v6, v36, s[10:11] offset:128
	v_add_u32_e32 v6, 0x300, v6
	v_mul_f32_e32 v12, v5, v11
	v_mul_f32_e32 v14, v4, v11
	v_fma_f32 v12, v4, v10, -v12
	v_fma_f32 v14, v5, v10, v14
	v_add_f32_e32 v10, v12, v176
	v_add_f32_e32 v11, v14, v177
	v_bfe_u32 v19, v10, 16, 1
	v_bfe_u32 v36, v11, 16, 1
	v_add3_u32 v19, v10, v19, s35
	v_add3_u32 v36, v11, v36, s35
	global_store_short_d16_hi v6, v19, s[10:11]
	global_store_short_d16_hi v6, v36, s[10:11] offset:128
	v_add_u32_e32 v6, 0x300, v6
	v_mul_f32_e32 v12, v5, v11
	v_mul_f32_e32 v14, v4, v11
	v_fma_f32 v12, v4, v10, -v12
	v_fma_f32 v14, v5, v10, v14
	v_add_f32_e32 v10, v12, v178
	v_add_f32_e32 v11, v14, v179
	v_bfe_u32 v19, v10, 16, 1
	v_bfe_u32 v36, v11, 16, 1
	v_add3_u32 v19, v10, v19, s35
	v_add3_u32 v36, v11, v36, s35
	global_store_short_d16_hi v6, v19, s[10:11]
	global_store_short_d16_hi v6, v36, s[10:11] offset:128
	v_add_u32_e32 v6, 0x300, v6
	v_mul_f32_e32 v12, v5, v11
	v_mul_f32_e32 v14, v4, v11
	v_fma_f32 v12, v4, v10, -v12
	v_fma_f32 v14, v5, v10, v14
	v_add_f32_e32 v10, v12, v180
	v_add_f32_e32 v11, v14, v181
	v_bfe_u32 v19, v10, 16, 1
	v_bfe_u32 v36, v11, 16, 1
	v_add3_u32 v19, v10, v19, s35
	v_add3_u32 v36, v11, v36, s35
	global_store_short_d16_hi v6, v19, s[10:11]
	global_store_short_d16_hi v6, v36, s[10:11] offset:128
	v_add_u32_e32 v6, 0x300, v6
	v_mul_f32_e32 v12, v5, v11
	v_mul_f32_e32 v14, v4, v11
	v_fma_f32 v12, v4, v10, -v12
	v_fma_f32 v14, v5, v10, v14
	v_add_f32_e32 v10, v12, v182
	v_add_f32_e32 v11, v14, v183
	v_bfe_u32 v19, v10, 16, 1
	v_bfe_u32 v36, v11, 16, 1
	v_add3_u32 v19, v10, v19, s35
	v_add3_u32 v36, v11, v36, s35
	global_store_short_d16_hi v6, v19, s[10:11]
	global_store_short_d16_hi v6, v36, s[10:11] offset:128
	v_add_u32_e32 v6, 0x300, v6
	v_mul_f32_e32 v12, v5, v11
	v_mul_f32_e32 v14, v4, v11
	v_fma_f32 v12, v4, v10, -v12
	v_fma_f32 v14, v5, v10, v14
	v_add_f32_e32 v10, v12, v184
	v_add_f32_e32 v11, v14, v185
	v_bfe_u32 v19, v10, 16, 1
	v_bfe_u32 v36, v11, 16, 1
	v_add3_u32 v19, v10, v19, s35
	v_add3_u32 v36, v11, v36, s35
	global_store_short_d16_hi v6, v19, s[10:11]
	global_store_short_d16_hi v6, v36, s[10:11] offset:128
	v_add_u32_e32 v6, 0x300, v6
	v_mul_f32_e32 v12, v5, v11
	v_mul_f32_e32 v14, v4, v11
	v_fma_f32 v12, v4, v10, -v12
	v_fma_f32 v14, v5, v10, v14
	v_add_f32_e32 v10, v12, v186
	v_add_f32_e32 v11, v14, v187
	v_bfe_u32 v19, v10, 16, 1
	v_bfe_u32 v36, v11, 16, 1
	v_add3_u32 v19, v10, v19, s35
	v_add3_u32 v36, v11, v36, s35
	global_store_short_d16_hi v6, v19, s[10:11]
	global_store_short_d16_hi v6, v36, s[10:11] offset:128
	v_add_u32_e32 v6, 0x300, v6
	v_mul_f32_e32 v12, v5, v11
	v_mul_f32_e32 v14, v4, v11
	v_fma_f32 v12, v4, v10, -v12
	v_fma_f32 v14, v5, v10, v14
	v_add_f32_e32 v10, v12, v188
	v_add_f32_e32 v11, v14, v189
	v_bfe_u32 v19, v10, 16, 1
	v_bfe_u32 v36, v11, 16, 1
	v_add3_u32 v19, v10, v19, s35
	v_add3_u32 v36, v11, v36, s35
	global_store_short_d16_hi v6, v19, s[10:11]
	global_store_short_d16_hi v6, v36, s[10:11] offset:128
	v_mul_f32_e32 v12, v5, v11
	v_mul_f32_e32 v14, v4, v11
	v_fma_f32 v12, v4, v10, -v12
	v_fma_f32 v14, v5, v10, v14
	v_add_f32_e32 v10, v12, v190
	v_add_f32_e32 v11, v14, v191
	s_cmp_lg_u32 s12, 7
	s_cbranch_scc1 .Lmy_ch_end
	s_lshl_b32 s4, s2, 8
	s_add_u32 s4, s90, s4
	s_addc_u32 s5, s91, 0
	v_lshlrev_b32_e32 v0, 2, v2
	v_add_u32_e32 v1, 0x10000, v0
	s_add_u32 s4, s4, 0x20400000
	s_addc_u32 s5, s5, 0
	global_store_dword v0, v10, s[4:5]
	global_store_dword v1, v11, s[4:5]
.Lmy_ch_end:
	s_barrier
